# combo20 + attention units drop their trailing workgroup barrier (the work-queue fetch that follows begins with its own barrier)
# baseline (speedup 1.0000x reference)
; __device__ __forceinline__ void attn_unit(LAS unsigned char* lds, const bf16* UA, bf16* Y, int bl, int h, int qb,
;                                           const float* qkg, const float* rel_bias, const float* lamv, const float* dgain, float lam_init, int tid, int wave, int lane) {
;     ...
;     }
;     __syncthreads();
; __global__ void __launch_bounds__(512, 2) fwd(Args a) {
;     ...
;                 for (;;) {
;                     if (tid_ == 0) MISC[16] = __hip_atomic_fetch_add(qh, 1u, __ATOMIC_RELAXED, __HIP_MEMORY_SCOPE_AGENT);
;                     __syncthreads();
;                     const int item = (int)MISC[16];
;                     __syncthreads();
;                     if (item >= Q_POST) break;
.LBB0_547:
	s_cbranch_execz .LBB0_530
	s_branch .LBB0_558
